# P8 residual epilogue: 32 serialized load-wait-fma-store round trips pipelined 4 deep (fresh VGPR ring v240-255, precomputed row-group addresses, counted vmcnt); plus P7 Hs ladder hoist
# speedup vs baseline: 1.0062x; 1.0062x over previous
;     __device__ __forceinline__ void operator()(const f32x4 (&acc)[2][2][4][2], const Unit& u, int wr, int wc, int fr, int fq) const {
;         const int row0 = u.pm * BM + wr * 64 + fr; const int col0 = u.pn * BM + wc * 32 + 4 * fq;
; #pragma unroll
;         for (int ai = 0; ai < 2; ++ai)
; #pragma unroll
;             for (int m = 0; m < 4; ++m) { const size_t off = (size_t)(row0 + ai * HALF + m * 16) * D + col0;
; #pragma unroll
;                 for (int bj = 0; bj < 2; ++bj)
; #pragma unroll
;                     for (int n = 0; n < 2; ++n) { const size_t o = off + bj * HALF + n * 16; const f32x4 rv = *(const f32x4*)(res + o); *(f32x4*)(out + o) = rv * alpha + acc[ai][bj][m][n] * s; } }
;     }
.LBB0_719:
	v_lshl_add_u32 v146, s26, 8, v148
	v_lshl_or_b32 v142, s27, 8, v150
	v_ashrrev_i32_e32 v147, 31, v146
	v_ashrrev_i32_e32 v143, 31, v142
	v_lshlrev_b64 v[144:145], 12, v[146:147]
	v_lshl_add_u64 v[154:155], s[84:85], 0, v[144:145]
	v_lshlrev_b64 v[144:145], 2, v[142:143]
	v_lshl_add_u64 v[142:143], v[154:155], 0, v[144:145]
	s_mov_b64 s[26:27], -1
	v_add_co_u32_e32 v224, vcc, 0x10000, v142
	s_nop 0
	v_addc_co_u32_e32 v225, vcc, 0, v143, vcc
	v_add_co_u32_e32 v226, vcc, 0x20000, v142
	s_nop 0
	v_addc_co_u32_e32 v227, vcc, 0, v143, vcc
	v_add_co_u32_e32 v228, vcc, 0x30000, v142
	s_nop 0
	v_addc_co_u32_e32 v229, vcc, 0, v143, vcc
	v_add_co_u32_e32 v230, vcc, 0x80000, v142
	s_nop 0
	v_addc_co_u32_e32 v231, vcc, 0, v143, vcc
	v_add_co_u32_e32 v232, vcc, 0x90000, v142
	s_nop 0
	v_addc_co_u32_e32 v233, vcc, 0, v143, vcc
	v_add_co_u32_e32 v234, vcc, 0xa0000, v142
	s_nop 0
	v_addc_co_u32_e32 v235, vcc, 0, v143, vcc
	v_add_co_u32_e32 v236, vcc, 0xb0000, v142
	s_nop 0
	v_addc_co_u32_e32 v237, vcc, 0, v143, vcc
	global_load_dwordx4 v[240:243], v[142:143], off
	global_load_dwordx4 v[244:247], v[142:143], off offset:64
	global_load_dwordx4 v[248:251], v[142:143], off offset:512
	global_load_dwordx4 v[252:255], v[142:143], off offset:576
	s_waitcnt vmcnt(3)
	v_pk_fma_f32 v[128:129], v[242:243], s[8:9], v[128:129] op_sel_hi:[1,0,1]
	v_pk_fma_f32 v[126:127], v[240:241], s[8:9], v[126:127] op_sel_hi:[1,0,1]
	global_store_dwordx4 v[142:143], v[126:129], off
	global_load_dwordx4 v[240:243], v[224:225], off
	s_waitcnt vmcnt(4)
	v_pk_fma_f32 v[124:125], v[246:247], s[8:9], v[124:125] op_sel_hi:[1,0,1]
	v_pk_fma_f32 v[122:123], v[244:245], s[8:9], v[122:123] op_sel_hi:[1,0,1]
	global_store_dwordx4 v[142:143], v[122:125], off offset:64
	global_load_dwordx4 v[244:247], v[224:225], off offset:64
	s_waitcnt vmcnt(5)
	v_pk_fma_f32 v[120:121], v[250:251], s[8:9], v[120:121] op_sel_hi:[1,0,1]
	v_pk_fma_f32 v[118:119], v[248:249], s[8:9], v[118:119] op_sel_hi:[1,0,1]
	global_store_dwordx4 v[142:143], v[118:121], off offset:512
	global_load_dwordx4 v[248:251], v[224:225], off offset:512
	s_waitcnt vmcnt(6)
	v_pk_fma_f32 v[112:113], v[254:255], s[8:9], v[112:113] op_sel_hi:[1,0,1]
	v_pk_fma_f32 v[110:111], v[252:253], s[8:9], v[110:111] op_sel_hi:[1,0,1]
	global_store_dwordx4 v[142:143], v[110:113], off offset:576
	global_load_dwordx4 v[252:255], v[224:225], off offset:576
	s_waitcnt vmcnt(6)
	s_nop 1
	v_pk_fma_f32 v[112:113], v[242:243], s[8:9], v[116:117] op_sel_hi:[1,0,1]
	s_nop 1
	v_pk_fma_f32 v[110:111], v[240:241], s[8:9], v[114:115] op_sel_hi:[1,0,1]
	global_store_dwordx4 v[224:225], v[110:113], off
	global_load_dwordx4 v[240:243], v[226:227], off
	s_waitcnt vmcnt(6)
	v_pk_fma_f32 v[108:109], v[246:247], s[8:9], v[108:109] op_sel_hi:[1,0,1]
	v_pk_fma_f32 v[106:107], v[244:245], s[8:9], v[106:107] op_sel_hi:[1,0,1]
	global_store_dwordx4 v[224:225], v[106:109], off offset:64
	global_load_dwordx4 v[244:247], v[226:227], off offset:64
	s_waitcnt vmcnt(6)
	v_pk_fma_f32 v[104:105], v[250:251], s[8:9], v[104:105] op_sel_hi:[1,0,1]
	v_pk_fma_f32 v[102:103], v[248:249], s[8:9], v[102:103] op_sel_hi:[1,0,1]
	global_store_dwordx4 v[224:225], v[102:105], off offset:512
	global_load_dwordx4 v[248:251], v[226:227], off offset:512
	s_waitcnt vmcnt(6)
	v_pk_fma_f32 v[100:101], v[254:255], s[8:9], v[100:101] op_sel_hi:[1,0,1]
	v_pk_fma_f32 v[98:99], v[252:253], s[8:9], v[98:99] op_sel_hi:[1,0,1]
	global_store_dwordx4 v[224:225], v[98:101], off offset:576
	global_load_dwordx4 v[252:255], v[226:227], off offset:576
	s_waitcnt vmcnt(6)
	v_pk_fma_f32 v[96:97], v[242:243], s[8:9], v[96:97] op_sel_hi:[1,0,1]
	v_pk_fma_f32 v[94:95], v[240:241], s[8:9], v[94:95] op_sel_hi:[1,0,1]
	global_store_dwordx4 v[226:227], v[94:97], off
	global_load_dwordx4 v[240:243], v[228:229], off
	s_waitcnt vmcnt(6)
	v_pk_fma_f32 v[92:93], v[246:247], s[8:9], v[92:93] op_sel_hi:[1,0,1]
	v_pk_fma_f32 v[90:91], v[244:245], s[8:9], v[90:91] op_sel_hi:[1,0,1]
	global_store_dwordx4 v[226:227], v[90:93], off offset:64
	global_load_dwordx4 v[244:247], v[228:229], off offset:64
	s_waitcnt vmcnt(6)
	v_pk_fma_f32 v[88:89], v[250:251], s[8:9], v[88:89] op_sel_hi:[1,0,1]
	v_pk_fma_f32 v[86:87], v[248:249], s[8:9], v[86:87] op_sel_hi:[1,0,1]
	global_store_dwordx4 v[226:227], v[86:89], off offset:512
	global_load_dwordx4 v[248:251], v[228:229], off offset:512
	s_waitcnt vmcnt(6)
	v_pk_fma_f32 v[84:85], v[254:255], s[8:9], v[84:85] op_sel_hi:[1,0,1]
	v_pk_fma_f32 v[82:83], v[252:253], s[8:9], v[82:83] op_sel_hi:[1,0,1]
	global_store_dwordx4 v[226:227], v[82:85], off offset:576
	global_load_dwordx4 v[252:255], v[228:229], off offset:576
	s_waitcnt vmcnt(6)
	v_pk_fma_f32 v[80:81], v[242:243], s[8:9], v[80:81] op_sel_hi:[1,0,1]
	v_pk_fma_f32 v[78:79], v[240:241], s[8:9], v[78:79] op_sel_hi:[1,0,1]
	global_store_dwordx4 v[228:229], v[78:81], off
	global_load_dwordx4 v[240:243], v[230:231], off
	s_waitcnt vmcnt(6)
;     __device__ __forceinline__ void operator()(const f32x4 (&acc)[2][2][4][2], const Unit& u, int wr, int wc, int fr, int fq) const {
;         const int row0 = u.pm * BM + wr * 64 + fr; const int col0 = u.pn * BM + wc * 32 + 4 * fq;
; #pragma unroll
;         for (int ai = 0; ai < 2; ++ai)
; #pragma unroll
;             for (int m = 0; m < 4; ++m) { const size_t off = (size_t)(row0 + ai * HALF + m * 16) * D + col0;
; #pragma unroll
;                 for (int bj = 0; bj < 2; ++bj)
; #pragma unroll
;                     for (int n = 0; n < 2; ++n) { const size_t o = off + bj * HALF + n * 16; const f32x4 rv = *(const f32x4*)(res + o); *(f32x4*)(out + o) = rv * alpha + acc[ai][bj][m][n] * s; } }
;     }
	v_pk_fma_f32 v[76:77], v[246:247], s[8:9], v[76:77] op_sel_hi:[1,0,1]
	v_pk_fma_f32 v[74:75], v[244:245], s[8:9], v[74:75] op_sel_hi:[1,0,1]
	global_store_dwordx4 v[228:229], v[74:77], off offset:64
	global_load_dwordx4 v[244:247], v[230:231], off offset:64
	s_waitcnt vmcnt(6)
	v_pk_fma_f32 v[72:73], v[250:251], s[8:9], v[72:73] op_sel_hi:[1,0,1]
	v_pk_fma_f32 v[70:71], v[248:249], s[8:9], v[70:71] op_sel_hi:[1,0,1]
	global_store_dwordx4 v[228:229], v[70:73], off offset:512
	global_load_dwordx4 v[248:251], v[230:231], off offset:512
	s_waitcnt vmcnt(6)
	v_pk_fma_f32 v[68:69], v[254:255], s[8:9], v[68:69] op_sel_hi:[1,0,1]
	v_pk_fma_f32 v[66:67], v[252:253], s[8:9], v[66:67] op_sel_hi:[1,0,1]
	global_store_dwordx4 v[228:229], v[66:69], off offset:576
	global_load_dwordx4 v[252:255], v[230:231], off offset:576
	s_waitcnt vmcnt(6)
	v_pk_fma_f32 v[64:65], v[242:243], s[8:9], v[64:65] op_sel_hi:[1,0,1]
	v_pk_fma_f32 v[62:63], v[240:241], s[8:9], v[62:63] op_sel_hi:[1,0,1]
	global_store_dwordx4 v[230:231], v[62:65], off
	global_load_dwordx4 v[240:243], v[232:233], off
	s_waitcnt vmcnt(6)
	v_pk_fma_f32 v[60:61], v[246:247], s[8:9], v[60:61] op_sel_hi:[1,0,1]
	v_pk_fma_f32 v[58:59], v[244:245], s[8:9], v[58:59] op_sel_hi:[1,0,1]
	global_store_dwordx4 v[230:231], v[58:61], off offset:64
	global_load_dwordx4 v[244:247], v[232:233], off offset:64
	s_waitcnt vmcnt(6)
	v_pk_fma_f32 v[56:57], v[250:251], s[8:9], v[56:57] op_sel_hi:[1,0,1]
	v_pk_fma_f32 v[54:55], v[248:249], s[8:9], v[54:55] op_sel_hi:[1,0,1]
	global_store_dwordx4 v[230:231], v[54:57], off offset:512
	global_load_dwordx4 v[248:251], v[232:233], off offset:512
	s_waitcnt vmcnt(6)
	v_pk_fma_f32 v[52:53], v[254:255], s[8:9], v[52:53] op_sel_hi:[1,0,1]
	v_pk_fma_f32 v[50:51], v[252:253], s[8:9], v[50:51] op_sel_hi:[1,0,1]
	global_store_dwordx4 v[230:231], v[50:53], off offset:576
	global_load_dwordx4 v[252:255], v[232:233], off offset:576
	s_waitcnt vmcnt(6)
	v_pk_fma_f32 v[48:49], v[242:243], s[8:9], v[48:49] op_sel_hi:[1,0,1]
	v_pk_fma_f32 v[46:47], v[240:241], s[8:9], v[46:47] op_sel_hi:[1,0,1]
	global_store_dwordx4 v[232:233], v[46:49], off
	global_load_dwordx4 v[240:243], v[234:235], off
	s_waitcnt vmcnt(6)
	v_pk_fma_f32 v[44:45], v[246:247], s[8:9], v[44:45] op_sel_hi:[1,0,1]
	v_pk_fma_f32 v[42:43], v[244:245], s[8:9], v[42:43] op_sel_hi:[1,0,1]
	global_store_dwordx4 v[232:233], v[42:45], off offset:64
	global_load_dwordx4 v[244:247], v[234:235], off offset:64
	s_waitcnt vmcnt(6)
	v_pk_fma_f32 v[40:41], v[250:251], s[8:9], v[40:41] op_sel_hi:[1,0,1]
	v_pk_fma_f32 v[38:39], v[248:249], s[8:9], v[38:39] op_sel_hi:[1,0,1]
	global_store_dwordx4 v[232:233], v[38:41], off offset:512
	global_load_dwordx4 v[248:251], v[234:235], off offset:512
	s_waitcnt vmcnt(6)
	v_pk_fma_f32 v[36:37], v[254:255], s[8:9], v[36:37] op_sel_hi:[1,0,1]
	v_pk_fma_f32 v[34:35], v[252:253], s[8:9], v[34:35] op_sel_hi:[1,0,1]
	global_store_dwordx4 v[232:233], v[34:37], off offset:576
	global_load_dwordx4 v[252:255], v[234:235], off offset:576
	s_waitcnt vmcnt(6)
	v_pk_fma_f32 v[32:33], v[242:243], s[8:9], v[32:33] op_sel_hi:[1,0,1]
	v_pk_fma_f32 v[30:31], v[240:241], s[8:9], v[30:31] op_sel_hi:[1,0,1]
	global_store_dwordx4 v[234:235], v[30:33], off
	global_load_dwordx4 v[240:243], v[236:237], off
	s_waitcnt vmcnt(6)
	v_pk_fma_f32 v[28:29], v[246:247], s[8:9], v[28:29] op_sel_hi:[1,0,1]
	v_pk_fma_f32 v[26:27], v[244:245], s[8:9], v[26:27] op_sel_hi:[1,0,1]
	global_store_dwordx4 v[234:235], v[26:29], off offset:64
	global_load_dwordx4 v[244:247], v[236:237], off offset:64
	s_waitcnt vmcnt(6)
	v_pk_fma_f32 v[24:25], v[250:251], s[8:9], v[24:25] op_sel_hi:[1,0,1]
	v_pk_fma_f32 v[22:23], v[248:249], s[8:9], v[22:23] op_sel_hi:[1,0,1]
	global_store_dwordx4 v[234:235], v[22:25], off offset:512
	global_load_dwordx4 v[248:251], v[236:237], off offset:512
	s_waitcnt vmcnt(6)
	v_pk_fma_f32 v[20:21], v[254:255], s[8:9], v[20:21] op_sel_hi:[1,0,1]
	v_pk_fma_f32 v[18:19], v[252:253], s[8:9], v[18:19] op_sel_hi:[1,0,1]
	global_store_dwordx4 v[234:235], v[18:21], off offset:576
	global_load_dwordx4 v[252:255], v[236:237], off offset:576
	s_waitcnt vmcnt(6)
	v_pk_fma_f32 v[16:17], v[242:243], s[8:9], v[16:17] op_sel_hi:[1,0,1]
	v_pk_fma_f32 v[14:15], v[240:241], s[8:9], v[14:15] op_sel_hi:[1,0,1]
	global_store_dwordx4 v[236:237], v[14:17], off
	s_waitcnt vmcnt(5)
	v_pk_fma_f32 v[12:13], v[246:247], s[8:9], v[12:13] op_sel_hi:[1,0,1]
	v_pk_fma_f32 v[10:11], v[244:245], s[8:9], v[10:11] op_sel_hi:[1,0,1]
	global_store_dwordx4 v[236:237], v[10:13], off offset:64
	s_waitcnt vmcnt(4)
	v_pk_fma_f32 v[8:9], v[250:251], s[8:9], v[8:9] op_sel_hi:[1,0,1]
	v_pk_fma_f32 v[6:7], v[248:249], s[8:9], v[6:7] op_sel_hi:[1,0,1]
	global_store_dwordx4 v[236:237], v[6:9], off offset:512
	s_waitcnt vmcnt(3)
	v_pk_fma_f32 v[4:5], v[254:255], s[8:9], v[4:5] op_sel_hi:[1,0,1]
	v_pk_fma_f32 v[2:3], v[252:253], s[8:9], v[2:3] op_sel_hi:[1,0,1]
	global_store_dwordx4 v[236:237], v[2:5], off offset:576
	s_andn2_b64 vcc, exec, s[0:1]
	s_cbranch_vccnz .LBB0_708
	s_andn2_b64 vcc, exec, s[2:3]
	s_cbranch_vccnz .LBB0_707
	s_barrier
	s_branch .LBB0_707
